# SB attention tile loop: all K fragments requested at the loop top, V^T fragments right behind the QK chain (no MFMA waits on a just-issued LDS read)
# speedup vs baseline: 1.0025x; 1.0025x over previous
; #define LAS __attribute__((address_space(3)))
; __device__ __forceinline__ int crow(int r, int hi) { return (r & 3) + 8 * (r >> 2) + 4 * hi; }
; __device__ __forceinline__ float softplus2(float y) { return fmaxf(y, 0.f) + lg2(1.0f + ex2(-fabsf(y))); }
; #define MFMA32(a, b, c) __builtin_amdgcn_mfma_f32_32x32x16_bf16((a), (b), (c), 0, 0, 0)
; template <bool MASK> __device__ __forceinline__ void sb_tile(f32x16& p0, f32x16& p1, float& carry, int kv0, int qpos, int hi) {
;     ...
;     for (int r = 0; r < 16; ++r) { float s0 = softplus2(p0[r]), s1 = softplus2(p1[r]);
;         if (MASK) { if (kv0 + crow(r, hi) >= qpos) s0 = 0.f; if (kv0 + 32 + crow(r, hi) >= qpos) s1 = 0.f; }
;         sp0[r] = s0; sp1[r] = s1; }
; __device__ __forceinline__ void attn_unit_sb(int b, int h, int qb, const bf16_t* __restrict__ Q, const bf16_t* __restrict__ K, const bf16_t* __restrict__ Vt, bf16_t* __restrict__ O, LAS unsigned char* lds) {
;     ...
;             for (int d0 = 0; d0 < ND; ++d0) { const bf16x8 a0 = *(const LAS bf16x8*)(kb + d0 * 32), a1 = *(const LAS bf16x8*)(kb + 32 * KP + d0 * 32);
;                 p0 = MFMA32(a0, qr[d0], p0); p1 = MFMA32(a1, qr[d0], p1); }
;             sb_tile<true>(p0, p1, carry, jt * 64, qpos, hi);
.LBB0_489:
	v_add_u32_e32 v14, 0, v198
	ds_read_b128 v[202:205], v14 offset:4608
	ds_read_b128 v[206:209], v14
	ds_read_b128 v[210:213], v14 offset:32
	ds_read_b128 v[214:217], v14 offset:4640
	ds_read_b128 v[218:221], v14 offset:64
	ds_read_b128 v[222:225], v14 offset:4672
	ds_read_b128 v[236:239], v14 offset:96
	ds_read_b128 v[2:5], v14 offset:4704
	s_add_i32 s5, s19, 32
	v_or_b32_e32 v197, s19, v101
	s_waitcnt lgkmcnt(7)
	v_mfma_f32_32x32x16_bf16 v[64:79], v[202:205], v[84:87], 0
	v_or_b32_e32 v199, s5, v108
	v_cmp_lt_i32_e64 s[58:59], v199, v104
	v_cmp_lt_i32_e64 s[6:7], v197, v105
	v_or_b32_e32 v197, s19, v109
	v_or_b32_e32 v199, s5, v110
	v_cmp_lt_i32_e64 s[60:61], v199, v104
	s_waitcnt lgkmcnt(6)
	v_mfma_f32_32x32x16_bf16 v[48:63], v[206:209], v[84:87], 0
	v_cmp_lt_i32_e64 s[44:45], v197, v105
	v_or_b32_e32 v197, s19, v111
	v_or_b32_e32 v199, s5, v112
	v_cmp_lt_i32_e64 s[62:63], v199, v104
	v_cmp_lt_i32_e64 s[46:47], v197, v105
	v_or_b32_e32 v197, s19, v113
	v_or_b32_e32 v199, s5, v114
	s_waitcnt lgkmcnt(5)
	v_mfma_f32_32x32x16_bf16 v[48:63], v[210:213], v[88:91], v[48:63]
	v_cmp_lt_i32_e64 s[64:65], v199, v104
	v_cmp_lt_i32_e64 s[48:49], v197, v105
	v_or_b32_e32 v197, s19, v115
	v_or_b32_e32 v199, s5, v116
	v_cmp_lt_i32_e64 s[66:67], v199, v104
	v_cmp_lt_i32_e64 s[50:51], v197, v105
	v_or_b32_e32 v197, s19, v117
	s_waitcnt lgkmcnt(4)
	v_mfma_f32_32x32x16_bf16 v[64:79], v[214:217], v[88:91], v[64:79]
	v_or_b32_e32 v199, s5, v118
	v_cmp_lt_i32_e64 s[68:69], v199, v104
	v_cmp_lt_i32_e64 s[52:53], v197, v105
	v_or_b32_e32 v197, s19, v119
	v_or_b32_e32 v199, s5, v120
	v_cmp_lt_i32_e64 s[70:71], v199, v104
	s_waitcnt lgkmcnt(3)
	v_mfma_f32_32x32x16_bf16 v[48:63], v[218:221], v[92:95], v[48:63]
	v_cmp_lt_i32_e64 s[54:55], v197, v105
	v_or_b32_e32 v197, s19, v121
	v_or_b32_e32 v199, s5, v122
	v_cmp_lt_i32_e64 s[72:73], v199, v104
	v_cmp_lt_i32_e64 s[56:57], v197, v105
	v_or_b32_e32 v197, s19, v123
	v_or_b32_e32 v199, s5, v124
	s_waitcnt lgkmcnt(2)
	v_mfma_f32_32x32x16_bf16 v[64:79], v[222:225], v[92:95], v[64:79]
	v_cmp_lt_i32_e64 s[74:75], v199, v104
	v_cmp_lt_i32_e64 s[76:77], v197, v105
	v_or_b32_e32 v197, s19, v125
	v_or_b32_e32 v199, s5, v126
	v_cmp_lt_i32_e64 s[78:79], v199, v104
	v_cmp_lt_i32_e64 s[80:81], v197, v105
	s_waitcnt lgkmcnt(1)
	v_mfma_f32_32x32x16_bf16 v[48:63], v[236:239], v[96:99], v[48:63]
	v_or_b32_e32 v197, s19, v127
	v_or_b32_e32 v199, s5, v128
	v_cmp_lt_i32_e64 s[82:83], v199, v104
	v_cmp_lt_i32_e64 s[84:85], v197, v105
	v_or_b32_e32 v197, s19, v129
	v_or_b32_e32 v199, s5, v130
	v_cmp_lt_i32_e64 s[86:87], v199, v104
	s_waitcnt lgkmcnt(0)
	v_mfma_f32_32x32x16_bf16 v[64:79], v[2:5], v[96:99], v[64:79]
	s_nop 2
	v_add_u32_e32 v226, 0xf800, v1
	v_add_u32_e32 v227, 0x10d00, v1
	ds_read2_b64 v[202:205], v226 offset0:128 offset1:130
	ds_read_b64 v[206:207], v227
	ds_read_b64 v[208:209], v227 offset:16
	ds_read2_b64 v[210:213], v226 offset0:132 offset1:134
	ds_read_b64 v[214:215], v227 offset:32
	ds_read_b64 v[216:217], v227 offset:48
	ds_read2_b64 v[218:221], v226 offset0:136 offset1:138
	ds_read_b64 v[222:223], v227 offset:64
	ds_read_b64 v[224:225], v227 offset:80
	ds_read2_b64 v[236:239], v226 offset0:140 offset1:142
	v_exp_f32_e64 v5, -|v49|
	v_exp_f32_e64 v2, -|v48|
	v_max_f32_e32 v9, v49, v49
	v_max_f32_e32 v9, 0, v9
	v_add_f32_e32 v5, 1.0, v5
	v_log_f32_e32 v7, v5
	v_add_f32_e32 v2, 1.0, v2
	s_nop 1
	v_max_f32_e32 v5, v65, v65
	v_max_f32_e32 v8, 0, v5
	v_exp_f32_e64 v5, -|v65|
	v_log_f32_e32 v3, v2
	v_max_f32_e32 v2, v64, v64
	v_max_f32_e32 v4, 0, v2
	v_add_f32_e32 v5, 1.0, v5
	v_log_f32_e32 v6, v5
	v_exp_f32_e64 v5, -|v50|
	v_exp_f32_e64 v2, -|v64|
	v_max_f32_e32 v13, v50, v50
	v_max_f32_e32 v13, 0, v13
	v_add_f32_e32 v5, 1.0, v5
	v_log_f32_e32 v11, v5
	v_max_f32_e32 v5, v66, v66
	v_max_f32_e32 v12, 0, v5
	v_exp_f32_e64 v5, -|v66|
	v_add_f32_e32 v2, 1.0, v2
	v_log_f32_e32 v2, v2
	v_max_f32_e32 v141, v51, v51
	v_add_f32_e32 v5, 1.0, v5
	v_log_f32_e32 v10, v5
	v_exp_f32_e64 v5, -|v51|
	v_max_f32_e32 v141, 0, v141
	v_max_f32_e32 v145, v52, v52
	v_max_f32_e32 v161, v56, v56
	v_add_f32_e32 v5, 1.0, v5
	v_log_f32_e32 v15, v5
	v_max_f32_e32 v5, v67, v67
	v_max_f32_e32 v140, 0, v5
	v_exp_f32_e64 v5, -|v67|
	v_max_f32_e32 v145, 0, v145
	v_max_f32_e32 v149, v53, v53
	v_max_f32_e32 v161, 0, v161
	v_add_f32_e32 v5, 1.0, v5
	v_log_f32_e32 v14, v5
	v_exp_f32_e64 v5, -|v52|
	v_max_f32_e32 v165, v57, v57
	v_max_f32_e32 v149, 0, v149
	v_max_f32_e32 v165, 0, v165
	v_add_f32_e32 v5, 1.0, v5
	v_log_f32_e32 v143, v5
	v_max_f32_e32 v5, v68, v68
	v_max_f32_e32 v144, 0, v5
	v_exp_f32_e64 v5, -|v68|
	v_max_f32_e32 v169, v58, v58
	v_max_f32_e32 v153, v54, v54
	v_max_f32_e32 v169, 0, v169
	v_add_f32_e32 v5, 1.0, v5
	v_log_f32_e32 v142, v5
	v_exp_f32_e64 v5, -|v53|
	v_max_f32_e32 v173, v59, v59
	v_max_f32_e32 v153, 0, v153
	v_max_f32_e32 v173, 0, v173
	v_add_f32_e32 v5, 1.0, v5
	v_log_f32_e32 v147, v5
	v_max_f32_e32 v5, v69, v69
	v_max_f32_e32 v148, 0, v5
	v_exp_f32_e64 v5, -|v69|
	v_max_f32_e32 v177, v60, v60
	v_max_f32_e32 v157, v55, v55
	v_max_f32_e32 v177, 0, v177
	v_add_f32_e32 v5, 1.0, v5
	v_log_f32_e32 v146, v5
	v_exp_f32_e64 v5, -|v54|
	v_max_f32_e32 v181, v61, v61
	v_cmp_lt_i32_e64 s[88:89], v197, v105
	v_or_b32_e32 v197, s19, v131
	v_add_f32_e32 v5, 1.0, v5
	v_log_f32_e32 v151, v5
	v_max_f32_e32 v5, v70, v70
	v_max_f32_e32 v152, 0, v5
	v_exp_f32_e64 v5, -|v70|
	v_or_b32_e32 v199, s5, v132
	v_max_f32_e32 v157, 0, v157
	v_max_f32_e32 v181, 0, v181
	v_add_f32_e32 v5, 1.0, v5
	v_log_f32_e32 v150, v5
	v_exp_f32_e64 v5, -|v55|
	v_max_f32_e32 v185, v62, v62
	v_cmp_lt_i32_e64 s[90:91], v199, v104
	v_cmp_lt_i32_e64 s[92:93], v197, v105
; __device__ __forceinline__ int crow(int r, int hi) { return (r & 3) + 8 * (r >> 2) + 4 * hi; }
; __device__ __forceinline__ float softplus2(float y) { return fmaxf(y, 0.f) + lg2(1.0f + ex2(-fabsf(y))); }
; template <bool MASK> __device__ __forceinline__ void sb_tile(f32x16& p0, f32x16& p1, float& carry, int kv0, int qpos, int hi) {
;     ...
;     for (int r = 0; r < 16; ++r) { float s0 = softplus2(p0[r]), s1 = softplus2(p1[r]);
;         if (MASK) { if (kv0 + crow(r, hi) >= qpos) s0 = 0.f; if (kv0 + 32 + crow(r, hi) >= qpos) s1 = 0.f; }
;         sp0[r] = s0; sp1[r] = s1; }
;     float tl0[4], tl1[4], bt0, bt1;
;     { float G[4], Go[4], T[4];
; #pragma unroll
;       for (int i = 0; i < 4; ++i) { sp1[4 * i + 2] += sp1[4 * i + 3]; sp1[4 * i + 1] += sp1[4 * i + 2]; sp1[4 * i] += sp1[4 * i + 1]; G[i] = sp1[4 * i]; }
; #pragma unroll
;       for (int i = 0; i < 4; ++i) { Go[i] = xhalf(G[i], hi); T[i] = G[i] + Go[i]; }
;       const float st2 = T[3], st1 = T[3] + T[2], st0 = st1 + T[1]; bt1 = st0 + T[0];
;       tl1[3] = carry + (hi ? 0.f : Go[3]); tl1[2] = carry + st2 + (hi ? 0.f : Go[2]); tl1[1] = carry + st1 + (hi ? 0.f : Go[1]); tl1[0] = carry + st0 + (hi ? 0.f : Go[0]); }
	v_add_f32_e32 v5, 1.0, v5
	v_log_f32_e32 v155, v5
	v_max_f32_e32 v5, v71, v71
	v_max_f32_e32 v156, 0, v5
	v_exp_f32_e64 v5, -|v71|
	v_or_b32_e32 v197, s19, v133
	v_or_b32_e32 v199, s5, v134
	v_max_f32_e32 v185, 0, v185
	v_add_f32_e32 v5, 1.0, v5
	v_log_f32_e32 v154, v5
	v_exp_f32_e64 v5, -|v56|
	v_max_f32_e32 v189, v63, v63
	v_cmp_lt_i32_e64 s[94:95], v199, v104
	v_cmp_lt_i32_e64 s[96:97], v197, v105
	v_add_f32_e32 v5, 1.0, v5
	v_log_f32_e32 v159, v5
	v_max_f32_e32 v5, v72, v72
	v_max_f32_e32 v160, 0, v5
	v_exp_f32_e64 v5, -|v72|
	v_or_b32_e32 v197, s19, v135
	v_or_b32_e32 v199, s5, v136
	s_mov_b32 s4, s10
	v_add_f32_e32 v5, 1.0, v5
	v_log_f32_e32 v158, v5
	v_exp_f32_e64 v5, -|v57|
	v_max_f32_e32 v189, 0, v189
	v_cmp_lt_i32_e64 s[8:9], v199, v104
	v_cmp_lt_i32_e64 s[10:11], v197, v105
	v_add_f32_e32 v5, 1.0, v5
	v_log_f32_e32 v163, v5
	v_max_f32_e32 v5, v73, v73
	v_max_f32_e32 v164, 0, v5
	v_exp_f32_e64 v5, -|v73|
	v_or_b32_e32 v197, s19, v137
	v_or_b32_e32 v199, s5, v138
	v_cmp_lt_i32_e64 s[12:13], v199, v104
	v_add_f32_e32 v5, 1.0, v5
	v_log_f32_e32 v162, v5
	v_exp_f32_e64 v5, -|v58|
	v_cmp_lt_i32_e32 vcc, v197, v105
	s_mov_b32 s5, 0x43200000
	v_add_u32_e32 v198, 0xffffdc00, v198
	v_add_f32_e32 v5, 1.0, v5
	v_log_f32_e32 v167, v5
	v_max_f32_e32 v5, v74, v74
	v_max_f32_e32 v168, 0, v5
	v_exp_f32_e64 v5, -|v74|
	s_nop 0
	v_add_f32_e32 v5, 1.0, v5
	v_log_f32_e32 v166, v5
	v_exp_f32_e64 v5, -|v59|
	s_nop 0
	v_add_f32_e32 v5, 1.0, v5
	v_log_f32_e32 v171, v5
	v_max_f32_e32 v5, v75, v75
	v_max_f32_e32 v172, 0, v5
	v_exp_f32_e64 v5, -|v75|
	s_nop 0
	v_add_f32_e32 v5, 1.0, v5
	v_log_f32_e32 v170, v5
	v_exp_f32_e64 v5, -|v60|
	s_nop 0
	v_add_f32_e32 v5, 1.0, v5
	v_log_f32_e32 v175, v5
	v_max_f32_e32 v5, v76, v76
	v_max_f32_e32 v176, 0, v5
	v_exp_f32_e64 v5, -|v76|
	s_nop 0
	v_add_f32_e32 v5, 1.0, v5
	v_log_f32_e32 v174, v5
	v_exp_f32_e64 v5, -|v61|
	s_nop 0
	v_add_f32_e32 v5, 1.0, v5
	v_log_f32_e32 v179, v5
	v_max_f32_e32 v5, v77, v77
	v_max_f32_e32 v180, 0, v5
	v_exp_f32_e64 v5, -|v77|
	s_nop 0
	v_add_f32_e32 v5, 1.0, v5
	v_log_f32_e32 v178, v5
	v_exp_f32_e64 v5, -|v62|
	s_nop 0
	v_add_f32_e32 v5, 1.0, v5
	v_log_f32_e32 v183, v5
	v_max_f32_e32 v5, v78, v78
	v_max_f32_e32 v184, 0, v5
	v_exp_f32_e64 v5, -|v78|
	s_nop 0
	v_add_f32_e32 v5, 1.0, v5
	v_log_f32_e32 v182, v5
	v_exp_f32_e64 v5, -|v63|
	s_nop 0
	v_add_f32_e32 v5, 1.0, v5
	v_log_f32_e32 v187, v5
	v_max_f32_e32 v5, v79, v79
	v_max_f32_e32 v188, 0, v5
	v_exp_f32_e64 v5, -|v79|
	s_nop 0
	v_add_f32_e32 v5, 1.0, v5
	v_log_f32_e32 v186, v5
	v_max_f32_e32 v5, v48, v48
	v_max_f32_e32 v5, 0, v5
	v_pk_add_f32 v[2:3], v[4:5], v[2:3]
	s_nop 0
	v_cndmask_b32_e64 v201, 0, v3, s[6:7]
	v_cndmask_b32_e64 v200, 0, v2, s[58:59]
	v_pk_add_f32 v[2:3], v[8:9], v[6:7]
	s_nop 0
	v_cndmask_b32_e64 v7, 0, v3, s[44:45]
	v_cndmask_b32_e64 v6, 0, v2, s[60:61]
	v_pk_add_f32 v[2:3], v[12:13], v[10:11]
	v_pk_add_f32 v[12:13], v[160:161], v[158:159]
	v_cndmask_b32_e64 v9, 0, v3, s[46:47]
	v_cndmask_b32_e64 v8, 0, v2, s[62:63]
	v_pk_add_f32 v[2:3], v[140:141], v[14:15]
	s_nop 0
	v_cndmask_b32_e64 v5, 0, v3, s[48:49]
	v_cndmask_b32_e64 v4, 0, v2, s[64:65]
	v_pk_add_f32 v[2:3], v[144:145], v[142:143]
	s_nop 0
	v_cndmask_b32_e64 v11, 0, v3, s[50:51]
	v_cndmask_b32_e64 v10, 0, v2, s[66:67]
	v_pk_add_f32 v[2:3], v[148:149], v[146:147]
	v_cndmask_b32_e64 v147, 0, v13, s[76:77]
	v_cndmask_b32_e64 v146, 0, v12, s[74:75]
	v_pk_add_f32 v[12:13], v[164:165], v[162:163]
	v_cndmask_b32_e64 v143, 0, v3, s[52:53]
	v_cndmask_b32_e64 v149, 0, v13, s[80:81]
	v_cndmask_b32_e64 v148, 0, v12, s[78:79]
	v_pk_add_f32 v[12:13], v[168:169], v[166:167]
	v_cndmask_b32_e64 v142, 0, v2, s[68:69]
	v_pk_add_f32 v[2:3], v[152:153], v[150:151]
	v_cndmask_b32_e64 v151, 0, v13, s[84:85]
	v_cndmask_b32_e64 v150, 0, v12, s[82:83]
	v_pk_add_f32 v[12:13], v[172:173], v[170:171]
	v_cndmask_b32_e64 v145, 0, v3, s[54:55]
	v_cndmask_b32_e64 v153, 0, v13, s[88:89]
	v_cndmask_b32_e64 v152, 0, v12, s[86:87]
	v_pk_add_f32 v[12:13], v[176:177], v[174:175]
	v_cndmask_b32_e64 v144, 0, v2, s[70:71]
	v_pk_add_f32 v[2:3], v[156:157], v[154:155]
	v_cndmask_b32_e64 v155, 0, v13, s[92:93]
	v_cndmask_b32_e64 v154, 0, v12, s[90:91]
	v_pk_add_f32 v[12:13], v[180:181], v[178:179]
	v_pk_add_f32 v[150:151], v[150:151], v[152:153]
	v_cndmask_b32_e64 v157, 0, v13, s[96:97]
	v_cndmask_b32_e64 v156, 0, v12, s[94:95]
	v_pk_add_f32 v[12:13], v[184:185], v[182:183]
	v_cndmask_b32_e64 v3, 0, v3, s[56:57]
	v_cndmask_b32_e64 v159, 0, v13, s[10:11]
	v_cndmask_b32_e64 v158, 0, v12, s[8:9]
	v_pk_add_f32 v[12:13], v[188:189], v[186:187]
	v_cndmask_b32_e64 v2, 0, v2, s[72:73]
	v_cndmask_b32_e32 v161, 0, v13, vcc
	v_cndmask_b32_e64 v160, 0, v12, s[12:13]
	v_pk_add_f32 v[158:159], v[158:159], v[160:161]
	v_pk_add_f32 v[12:13], v[8:9], v[4:5]
	v_pk_add_f32 v[156:157], v[156:157], v[158:159]
	v_pk_add_f32 v[162:163], v[148:149], v[150:151]
	v_pk_add_f32 v[154:155], v[154:155], v[156:157]
	v_pk_add_f32 v[14:15], v[6:7], v[12:13]
	v_pk_add_f32 v[6:7], v[144:145], v[2:3]
	v_pk_add_f32 v[164:165], v[146:147], v[162:163]
	v_mov_b32_e32 v145, v154
	v_mov_b32_e32 v146, v154
	v_mov_b32_e32 v147, v155
	v_mov_b32_e32 v148, v155
	v_pk_add_f32 v[8:9], v[142:143], v[6:7]
	v_mov_b32_e32 v142, v164
	v_mov_b32_e32 v143, v164
	v_permlane32_swap_b32_e32 v145, v146
	v_permlane32_swap_b32_e32 v147, v148
	v_permlane32_swap_b32_e32 v142, v143
	v_cndmask_b32_e64 v167, v147, v148, s[40:41]
	v_cndmask_b32_e64 v166, v145, v146, s[40:41]
	v_mov_b32_e32 v146, v165
	v_mov_b32_e32 v147, v165
	v_pk_add_f32 v[10:11], v[10:11], v[8:9]
	v_cndmask_b32_e64 v145, 0, v166, s[40:41]
	v_pk_add_f32 v[168:169], v[154:155], v[166:167]
; __device__ __forceinline__ unsigned pk2(float lo, float hi) { f32x2_t v = {lo, hi}; bf16x2_t b = __builtin_convertvector(v, bf16x2_t); return __builtin_bit_cast(unsigned, b); }
; template <bool MASK> __device__ __forceinline__ void sb_tile(f32x16& p0, f32x16& p1, float& carry, int kv0, int qpos, int hi) {
;     ...
;       for (int i = 0; i < 4; ++i) { Go[i] = xhalf(G[i], hi); T[i] = G[i] + Go[i]; }
;       const float st2 = T[3], st1 = T[3] + T[2], st0 = st1 + T[1]; bt1 = st0 + T[0];
;       tl1[3] = carry + (hi ? 0.f : Go[3]); tl1[2] = carry + st2 + (hi ? 0.f : Go[2]); tl1[1] = carry + st1 + (hi ? 0.f : Go[1]); tl1[0] = carry + st0 + (hi ? 0.f : Go[0]); }
;     { float G[4], Go[4], T[4]; const float base = carry + bt1;
; #pragma unroll
;       for (int i = 0; i < 4; ++i) { sp0[4 * i + 2] += sp0[4 * i + 3]; sp0[4 * i + 1] += sp0[4 * i + 2]; sp0[4 * i] += sp0[4 * i + 1]; G[i] = sp0[4 * i]; }
; #pragma unroll
;       for (int i = 0; i < 4; ++i) { Go[i] = xhalf(G[i], hi); T[i] = G[i] + Go[i]; }
;       const float st2 = T[3], st1 = T[3] + T[2], st0 = st1 + T[1]; bt0 = st0 + T[0];
;       tl0[3] = base + (hi ? 0.f : Go[3]); tl0[2] = base + st2 + (hi ? 0.f : Go[2]); tl0[1] = base + st1 + (hi ? 0.f : Go[1]); tl0[0] = base + st0 + (hi ? 0.f : Go[0]); }
;     carry += bt0 + bt1;
; #pragma unroll
;     for (int r = 0; r < 16; ++r) { float w0 = ex2(p0[r] - (sp0[r] + tl0[r >> 2])), w1 = ex2(p1[r] - (sp1[r] + tl1[r >> 2]));
;         if (MASK) { if (kv0 + crow(r, hi) >= qpos) w0 = 0.f; if (kv0 + 32 + crow(r, hi) >= qpos) w1 = 0.f; }
;         p0[r] = w0; p1[r] = w1; }
; __device__ __forceinline__ void attn_unit_sb(int b, int h, int qb, const bf16_t* __restrict__ Q, const bf16_t* __restrict__ K, const bf16_t* __restrict__ Vt, bf16_t* __restrict__ O, LAS unsigned char* lds) {
;     ...
;             for (int j = 0; j < 4; ++j) {
;                 u32x4 pw;
;                 if (j < 2) { const int r0 = 8 * (j & 1); pw.x = pk2(p0[r0], p0[r0 + 1]); pw.y = pk2(p0[r0 + 2], p0[r0 + 3]); pw.z = pk2(p0[r0 + 4], p0[r0 + 5]); pw.w = pk2(p0[r0 + 6], p0[r0 + 7]); }
;                 else { const int r0 = 8 * (j & 1); pw.x = pk2(p1[r0], p1[r0 + 1]); pw.y = pk2(p1[r0 + 2], p1[r0 + 3]); pw.z = pk2(p1[r0 + 4], p1[r0 + 5]); pw.w = pk2(p1[r0 + 6], p1[r0 + 7]); }
;                 const bf16x8 pa = __builtin_bit_cast(bf16x8, pw);
	v_permlane32_swap_b32_e32 v146, v147
	v_cndmask_b32_e64 v170, v142, v143, s[40:41]
	v_mov_b32_e32 v144, v10
	v_mov_b32_e32 v174, v10
	v_add_f32_e32 v175, v195, v145
	v_add_f32_e32 v145, v195, v168
	v_cndmask_b32_e64 v171, v146, v147, s[40:41]
	v_cndmask_b32_e64 v142, 0, v170, s[40:41]
	v_permlane32_swap_b32_e32 v144, v174
	v_add_f32_e32 v166, v142, v145
	v_pk_add_f32 v[142:143], v[164:165], v[170:171]
	v_mov_b32_e32 v145, v11
	v_mov_b32_e32 v147, v11
	v_pk_add_f32 v[142:143], v[142:143], v[168:169]
	s_nop 0
	v_permlane32_swap_b32_e32 v145, v147
	v_cndmask_b32_e64 v144, v144, v174, s[40:41]
	v_pk_add_f32 v[140:141], v[200:201], v[14:15]
	v_add_f32_e32 v146, v195, v142
	v_cndmask_b32_e64 v145, v145, v147, s[40:41]
	v_cndmask_b32_e64 v147, 0, v144, s[40:41]
	v_mov_b32_e32 v172, v140
	v_mov_b32_e32 v173, v140
	v_add_f32_e32 v168, v147, v146
	v_pk_add_f32 v[146:147], v[10:11], v[144:145]
	v_mov_b32_e32 v144, v141
	v_mov_b32_e32 v148, v141
	v_permlane32_swap_b32_e32 v172, v173
	s_nop 0
	v_permlane32_swap_b32_e32 v144, v148
	v_cndmask_b32_e64 v149, v144, v148, s[40:41]
	v_cndmask_b32_e64 v148, v172, v173, s[40:41]
	v_pk_add_f32 v[146:147], v[146:147], v[142:143]
	v_pk_add_f32 v[172:173], v[140:141], v[148:149]
	v_add_f32_e32 v142, v195, v146
	v_cndmask_b32_e64 v144, 0, v148, s[40:41]
	v_pk_add_f32 v[172:173], v[172:173], v[146:147]
	v_add_f32_e32 v170, v144, v142
	v_add_f32_e32 v144, v195, v172
	v_cndmask_b32_e64 v142, 0, v167, s[40:41]
	v_add_f32_e32 v146, v142, v144
	v_add_f32_e32 v142, v169, v144
	v_cndmask_b32_e64 v148, 0, v171, s[40:41]
	v_add_f32_e32 v148, v148, v142
	v_add_f32_e32 v14, v14, v170
	v_sub_f32_e32 v14, v65, v14
	v_add_f32_e32 v65, v165, v148
	v_sub_f32_e32 v56, v56, v65
	v_add_f32_e32 v65, v164, v166
	v_add_f32_e32 v12, v12, v170
	v_sub_f32_e32 v65, v72, v65
	v_sub_f32_e32 v12, v66, v12
	v_exp_f32_e32 v56, v56
	v_exp_f32_e32 v66, v65
	v_add_f32_e32 v4, v4, v170
	v_sub_f32_e32 v4, v67, v4
	v_cndmask_b32_e64 v65, 0, v56, s[76:77]
	v_cndmask_b32_e64 v56, 0, v66, s[74:75]
	v_add_f32_e32 v66, v163, v148
	v_sub_f32_e32 v57, v57, v66
	v_add_f32_e32 v66, v162, v166
	v_sub_f32_e32 v66, v73, v66
	v_exp_f32_e32 v57, v57
	v_exp_f32_e32 v67, v66
	v_add_f32_e32 v10, v10, v168
	v_sub_f32_e32 v10, v68, v10
	v_cndmask_b32_e64 v66, 0, v57, s[80:81]
	v_cndmask_b32_e64 v57, 0, v67, s[78:79]
	v_add_f32_e32 v67, v151, v148
	v_sub_f32_e32 v58, v58, v67
	v_add_f32_e32 v67, v150, v166
	v_sub_f32_e32 v67, v74, v67
	v_exp_f32_e32 v58, v58
	v_exp_f32_e32 v68, v67
	v_add_f32_e32 v8, v8, v168
	v_sub_f32_e32 v8, v69, v8
	v_cndmask_b32_e64 v67, 0, v58, s[84:85]
	v_cndmask_b32_e64 v58, 0, v68, s[82:83]
	v_add_f32_e32 v68, v153, v148
	v_sub_f32_e32 v59, v59, v68
	v_add_f32_e32 v68, v152, v166
	v_sub_f32_e32 v68, v75, v68
	v_exp_f32_e32 v59, v59
	v_exp_f32_e32 v69, v68
	v_add_f32_e32 v6, v6, v168
	v_sub_f32_e32 v6, v70, v6
	v_cndmask_b32_e64 v68, 0, v59, s[88:89]
	v_cndmask_b32_e64 v59, 0, v69, s[86:87]
	v_add_f32_e32 v69, v155, v146
	v_sub_f32_e32 v60, v60, v69
	v_add_f32_e32 v69, v175, v154
	v_sub_f32_e32 v69, v76, v69
	v_exp_f32_e32 v60, v60
	v_exp_f32_e32 v70, v69
	v_add_f32_e32 v2, v2, v168
	v_sub_f32_e32 v2, v71, v2
	v_cndmask_b32_e64 v69, 0, v60, s[92:93]
	v_cndmask_b32_e64 v60, 0, v70, s[90:91]
	v_add_f32_e32 v70, v157, v146
	v_sub_f32_e32 v61, v61, v70
	v_add_f32_e32 v70, v156, v175
	v_sub_f32_e32 v70, v77, v70
	v_exp_f32_e32 v61, v61
	v_exp_f32_e32 v71, v70
	v_cndmask_b32_e64 v74, 0, v149, s[40:41]
	v_add_f32_e32 v75, v147, v144
	v_add_f32_e32 v74, v74, v75
	v_add_f32_e32 v13, v13, v74
	v_add_f32_e32 v5, v5, v74
	v_cndmask_b32_e64 v70, 0, v61, s[96:97]
	v_cndmask_b32_e64 v61, 0, v71, s[94:95]
	v_add_f32_e32 v71, v159, v146
	v_sub_f32_e32 v13, v50, v13
	v_sub_f32_e32 v5, v51, v5
	v_sub_f32_e32 v62, v62, v71
	v_add_f32_e32 v71, v158, v175
	v_exp_f32_e32 v13, v13
	v_exp_f32_e32 v5, v5
	v_sub_f32_e32 v71, v78, v71
	v_exp_f32_e32 v62, v62
	v_exp_f32_e32 v72, v71
	v_add_f32_e32 v15, v15, v74
	v_cndmask_b32_e64 v13, 0, v13, s[46:47]
	v_cndmask_b32_e64 v5, 0, v5, s[48:49]
	v_sub_f32_e32 v15, v49, v15
	v_cvt_pk_bf16_f32 v49, v13, v5
	v_cndmask_b32_e64 v5, 0, v145, s[40:41]
	v_add_f32_e32 v13, v143, v144
	v_cndmask_b32_e64 v71, 0, v62, s[10:11]
	v_cndmask_b32_e64 v62, 0, v72, s[8:9]
	v_add_f32_e32 v72, v161, v146
	v_add_f32_e32 v5, v5, v13
	v_sub_f32_e32 v63, v63, v72
	v_add_f32_e32 v72, v160, v175
	v_add_f32_e32 v75, v141, v74
	v_add_f32_e32 v11, v11, v5
	v_add_f32_e32 v9, v9, v5
	v_add_f32_e32 v7, v7, v5
	v_add_f32_e32 v3, v3, v5
	v_sub_f32_e32 v72, v79, v72
	v_sub_f32_e32 v48, v48, v75
	v_sub_f32_e32 v11, v52, v11
	v_sub_f32_e32 v9, v53, v9
	v_sub_f32_e32 v7, v54, v7
	v_sub_f32_e32 v3, v55, v3
	v_exp_f32_e32 v63, v63
	v_exp_f32_e32 v73, v72
	v_exp_f32_e32 v48, v48
	v_exp_f32_e32 v15, v15
	v_exp_f32_e32 v11, v11
	v_exp_f32_e32 v9, v9
	v_exp_f32_e32 v7, v7
	v_exp_f32_e32 v3, v3
	v_cndmask_b32_e32 v72, 0, v63, vcc
	v_cndmask_b32_e64 v63, 0, v73, s[12:13]
	v_add_u32_e32 v73, 0, v1
	v_cndmask_b32_e64 v48, 0, v48, s[6:7]
	v_cndmask_b32_e64 v15, 0, v15, s[44:45]
	v_cndmask_b32_e64 v11, 0, v11, s[50:51]
	v_cndmask_b32_e64 v9, 0, v9, s[52:53]
	v_cndmask_b32_e64 v7, 0, v7, s[54:55]
	v_cndmask_b32_e64 v3, 0, v3, s[56:57]
	v_cvt_pk_bf16_f32 v48, v48, v15
	v_cvt_pk_bf16_f32 v50, v11, v9
	v_cvt_pk_bf16_f32 v51, v7, v3
	s_waitcnt lgkmcnt(0)
; #define LAS __attribute__((address_space(3)))
; __device__ __forceinline__ unsigned pk2(float lo, float hi) { f32x2_t v = {lo, hi}; bf16x2_t b = __builtin_convertvector(v, bf16x2_t); return __builtin_bit_cast(unsigned, b); }
; #define MFMA32(a, b, c) __builtin_amdgcn_mfma_f32_32x32x16_bf16((a), (b), (c), 0, 0, 0)
; __device__ __forceinline__ void attn_unit_sb(int b, int h, int qb, const bf16_t* __restrict__ Q, const bf16_t* __restrict__ K, const bf16_t* __restrict__ Vt, bf16_t* __restrict__ O, LAS unsigned char* lds) {
;     ...
;             for (int j = 0; j < 4; ++j) {
;                 u32x4 pw;
;                 if (j < 2) { const int r0 = 8 * (j & 1); pw.x = pk2(p0[r0], p0[r0 + 1]); pw.y = pk2(p0[r0 + 2], p0[r0 + 3]); pw.z = pk2(p0[r0 + 4], p0[r0 + 5]); pw.w = pk2(p0[r0 + 6], p0[r0 + 7]); }
;                 else { const int r0 = 8 * (j & 1); pw.x = pk2(p1[r0], p1[r0 + 1]); pw.y = pk2(p1[r0 + 2], p1[r0 + 3]); pw.z = pk2(p1[r0 + 4], p1[r0 + 5]); pw.w = pk2(p1[r0 + 6], p1[r0 + 7]); }
;                 const bf16x8 pa = __builtin_bit_cast(bf16x8, pw);
;                 { const s16x4 l4 = *(const LAS s16x4*)(vb + j * 32), hh = *(const LAS s16x4*)(vb + j * 32 + 16);
;                   const bf16x8 vf = {l4[0], l4[1], l4[2], l4[3], hh[0], hh[1], hh[2], hh[3]}; o0 = MFMA32(pa, vf, o0); }
;                 { const s16x4 l4 = *(const LAS s16x4*)(vb + 32 * VP + j * 32), hh = *(const LAS s16x4*)(vb + 32 * VP + j * 32 + 16);
;                   const bf16x8 vf = {l4[0], l4[1], l4[2], l4[3], hh[0], hh[1], hh[2], hh[3]}; o1 = MFMA32(pa, vf, o1); }
;             }
;             done = __all(carry > SB_DONE);
;         }
	s_nop 0
	v_mfma_f32_32x32x16_bf16 v[16:31], v[48:51], v[202:205], v[16:31]
	v_add_f32_e32 v140, v140, v170
	v_sub_f32_e32 v64, v64, v140
	v_exp_f32_e32 v64, v64
	v_exp_f32_e32 v14, v14
	v_mfma_f32_32x32x16_bf16 v[32:47], v[48:51], v[206:209], v[32:47]
	v_cvt_pk_bf16_f32 v48, v65, v66
	v_cvt_pk_bf16_f32 v49, v67, v68
	v_cvt_pk_bf16_f32 v50, v69, v70
	v_cvt_pk_bf16_f32 v51, v71, v72
	v_exp_f32_e32 v12, v12
	v_exp_f32_e32 v4, v4
	v_exp_f32_e32 v10, v10
	v_exp_f32_e32 v8, v8
	v_exp_f32_e32 v6, v6
	v_exp_f32_e32 v2, v2
	v_mfma_f32_32x32x16_bf16 v[16:31], v[48:51], v[210:213], v[16:31]
	v_cndmask_b32_e64 v64, 0, v64, s[58:59]
	v_cndmask_b32_e64 v14, 0, v14, s[60:61]
	v_cndmask_b32_e64 v12, 0, v12, s[62:63]
	v_cndmask_b32_e64 v4, 0, v4, s[64:65]
	v_cndmask_b32_e64 v10, 0, v10, s[66:67]
	v_cndmask_b32_e64 v8, 0, v8, s[68:69]
	v_cndmask_b32_e64 v6, 0, v6, s[70:71]
	v_cndmask_b32_e64 v2, 0, v2, s[72:73]
	v_mfma_f32_32x32x16_bf16 v[32:47], v[48:51], v[214:217], v[32:47]
	v_cvt_pk_bf16_f32 v48, v64, v14
	v_cvt_pk_bf16_f32 v49, v12, v4
	v_cvt_pk_bf16_f32 v50, v10, v8
	v_cvt_pk_bf16_f32 v51, v6, v2
	v_add_f32_e32 v142, v172, v173
	s_nop 0
	v_mfma_f32_32x32x16_bf16 v[16:31], v[48:51], v[218:221], v[16:31]
	v_add_f32_e32 v195, v195, v142
	v_cmp_lt_f32_e32 vcc, s5, v195
	s_cmp_eq_u64 vcc, exec
	v_mfma_f32_32x32x16_bf16 v[32:47], v[48:51], v[222:225], v[32:47]
	v_cvt_pk_bf16_f32 v2, v56, v57
	v_cvt_pk_bf16_f32 v3, v58, v59
	v_cvt_pk_bf16_f32 v4, v60, v61
	v_cvt_pk_bf16_f32 v5, v62, v63
	s_cselect_b64 s[6:7], -1, 0
	s_add_i32 s10, s4, -1
	s_cmp_le_u32 s4, s0
	v_mfma_f32_32x32x16_bf16 v[16:31], v[2:5], v[236:239], v[16:31]
	v_add_u32_e32 v6, 0x10d60, v73
	v_add_u32_e32 v8, 0x10d70, v73
	ds_read_b64 v[6:7], v6
	ds_read_b64 v[8:9], v8
	s_cselect_b64 s[4:5], -1, 0
	s_or_b64 s[8:9], s[4:5], s[6:7]
	s_sub_i32 s19, s19, 64
	s_waitcnt lgkmcnt(0)
	v_mfma_f32_32x32x16_bf16 v[32:47], v[2:5], v[6:9], v[32:47]
	v_add_u32_e32 v1, 0xffffde00, v1
	s_andn2_b64 vcc, exec, s[8:9]
	s_cbranch_vccnz .LBB0_489
	s_mov_b64 s[94:95], 0x100
	s_mov_b64 s[96:97], 0x2000
